# attfast: attention softmax reference starts at 0 (sink weight 2^sink folded into the running sum); while all lanes' reference is 0 the 32 packed subtractions before the exponentials are skipped (wave-
# speedup vs baseline: 1.0043x; 1.0043x over previous
.LBB0_305:
	v_lshl_add_u64 v[4:5], s[6:7], 0, v[178:179]
	v_mov_b64_e32 v[6:7], s[82:83]
	v_mad_u64_u32 v[8:9], s[8:9], v4, s85, v[6:7]
	v_mov_b32_e32 v4, v9
	s_lshl_b32 s11, s11, 6
	v_mad_u64_u32 v[4:5], s[8:9], v5, s85, v[4:5]
	v_mov_b32_e32 v9, v4
	s_lshl_b32 s80, s11, 1
	v_lshl_add_u64 v[4:5], v[8:9], 0, s[80:81]
	v_lshl_add_u64 v[4:5], v[4:5], 0, v[0:1]
	global_load_dwordx4 v[162:165], v[4:5], off offset:1024
	global_load_dwordx4 v[166:169], v[4:5], off offset:1280
	v_lshl_add_u64 v[4:5], s[6:7], 0, v[180:181]
	v_mad_u64_u32 v[6:7], s[6:7], v4, s85, v[6:7]
	v_mov_b32_e32 v4, v7
	v_mad_u64_u32 v[4:5], s[6:7], v5, s85, v[4:5]
	v_mov_b32_e32 v7, v4
	v_lshl_add_u64 v[4:5], v[6:7], 0, s[80:81]
	v_lshl_add_u64 v[4:5], v[4:5], 0, v[0:1]
	global_load_dwordx4 v[170:173], v[4:5], off offset:1024
	global_load_dwordx4 v[174:177], v[4:5], off offset:1280
	s_lshl_b32 s20, s10, 6
	s_add_i32 s24, s22, 0xffffff80
	s_add_i32 s25, s22, 0xbf
	s_add_i32 s26, s22, 0xffffffbf
	s_add_i32 s27, s22, 0x41
	v_lshlrev_b32_e32 v200, 3, v3
	v_mul_f32_e32 v186, 0x3fb8aa3b, v2
	v_lshlrev_b32_e32 v2, 2, v3
	v_lshrrev_b32_e32 v3, 2, v187
	s_add_u32 s6, s82, s80
	v_and_b32_e32 v183, 63, v187
	v_and_or_b32 v202, v3, 3, v2
	v_lshlrev_b32_e32 v3, 2, v187
	v_sub_u32_e32 v2, v2, v189
	s_addc_u32 s7, s83, 0
	v_mov_b32_e32 v14, v1
	v_mov_b32_e32 v15, v1
	v_cmp_gt_u32_e32 vcc, 32, v183
	v_and_b32_e32 v16, 16, v187
	v_and_b32_e32 v17, 12, v3
	v_add_u32_e32 v203, 0x80, v2
	v_lshl_add_u64 v[184:185], s[6:7], 0, v[0:1]
	v_mov_b32_e32 v0, v1
	v_mov_b32_e32 v2, v1
	v_mov_b32_e32 v3, v1
	v_mov_b32_e32 v4, v1
	v_mov_b32_e32 v5, v1
	v_mov_b32_e32 v6, v1
	v_mov_b32_e32 v7, v1
	v_mov_b32_e32 v8, v1
	v_mov_b32_e32 v9, v1
	v_mov_b32_e32 v10, v1
	v_mov_b32_e32 v11, v1
	v_mov_b32_e32 v12, v1
	v_mov_b32_e32 v13, v1
	v_mov_b64_e32 v[64:65], v[14:15]
	v_mov_b64_e32 v[32:33], v[14:15]
	v_mov_b64_e32 v[48:49], v[14:15]
	v_cndmask_b32_e64 v201, 0, 1.0, vcc
	v_lshlrev_b32_e32 v204, 1, v16
	v_lshlrev_b32_e32 v205, 1, v17
	v_mov_b64_e32 v[62:63], v[12:13]
	v_mov_b64_e32 v[60:61], v[10:11]
	v_mov_b64_e32 v[58:59], v[8:9]
	v_mov_b64_e32 v[56:57], v[6:7]
	v_mov_b64_e32 v[54:55], v[4:5]
	v_mov_b64_e32 v[52:53], v[2:3]
	v_mov_b64_e32 v[50:51], v[0:1]
	v_mov_b64_e32 v[30:31], v[12:13]
	v_mov_b64_e32 v[28:29], v[10:11]
	v_mov_b64_e32 v[26:27], v[8:9]
	v_mov_b64_e32 v[24:25], v[6:7]
	v_mov_b64_e32 v[22:23], v[4:5]
	v_mov_b64_e32 v[20:21], v[2:3]
	v_mov_b64_e32 v[18:19], v[0:1]
	v_mov_b64_e32 v[46:47], v[12:13]
	v_mov_b64_e32 v[44:45], v[10:11]
	v_mov_b64_e32 v[42:43], v[8:9]
	v_mov_b64_e32 v[40:41], v[6:7]
	v_mov_b64_e32 v[38:39], v[4:5]
	v_mov_b64_e32 v[36:37], v[2:3]
	v_mov_b64_e32 v[34:35], v[0:1]
	v_mov_b64_e32 v[16:17], v[14:15]
	s_mov_b32 s28, 0
	v_mov_b32_e32 v199, v201
	v_mov_b32_e32 v188, v186
	s_mov_b32 s99, 0x42800000
	v_exp_f32_e32 v220, v186
	v_cmp_lt_f32_e64 vcc, |v186|, s99
	s_nop 1
	v_cndmask_b32_e32 v220, 1.0, v220, vcc
	v_cndmask_b32_e64 v186, v186, 0, vcc
	v_mul_f32_e32 v201, v201, v220
	v_mov_b32_e32 v199, v201
	v_mov_b32_e32 v188, v186
	v_mov_b64_e32 v[14:15], v[12:13]
	v_mov_b64_e32 v[12:13], v[10:11]
	v_mov_b64_e32 v[10:11], v[8:9]
	v_mov_b64_e32 v[8:9], v[6:7]
	v_mov_b64_e32 v[6:7], v[4:5]
	v_mov_b64_e32 v[4:5], v[2:3]
	v_mov_b64_e32 v[2:3], v[0:1]
	s_waitcnt lgkmcnt(0)
	s_barrier
	v_readfirstlane_b32 s99, v244
	s_lshr_b32 s99, s99, 8
	s_cmp_eq_u32 s99, 1
	s_cbranch_scc0 .Lap_skip_mix2
	s_setprio 1

.LBB0_319:
	v_or_b32_e32 v221, s31, v202
	v_mad_u32_u24 v225, v221, s89, v206
	ds_read_b64_tr_b16 v[226:227], v225 offset:18432
	ds_read_b64_tr_b16 v[228:229], v225 offset:19584
	ds_read_b64_tr_b16 v[230:231], v225 offset:18496
	ds_read_b64_tr_b16 v[232:233], v225 offset:19648
	ds_read_b64_tr_b16 v[234:235], v225 offset:20736
	ds_read_b64_tr_b16 v[236:237], v225 offset:21888
	v_or_b32_e32 v220, v186, v188
	v_cmp_ne_u32_e32 vcc, 0, v220
	s_cbranch_vccnz .Laf_slow_mix2
	v_exp_f32_e32 v190, v114
	v_exp_f32_e32 v191, v115
	v_exp_f32_e32 v192, v116
	v_exp_f32_e32 v193, v117
	v_pk_add_f32 v[114:115], v[190:191], 0 op_sel_hi:[1,0]
	v_exp_f32_e32 v194, v118
	v_exp_f32_e32 v195, v119
	v_pk_add_f32 v[114:115], v[192:193], v[114:115]
	v_exp_f32_e32 v196, v120
	v_exp_f32_e32 v197, v121
	v_pk_add_f32 v[114:115], v[194:195], v[114:115]
	v_exp_f32_e32 v122, v122
	v_exp_f32_e32 v123, v123
	v_pk_add_f32 v[114:115], v[196:197], v[114:115]
	v_exp_f32_e32 v124, v124
	v_exp_f32_e32 v125, v125
	v_pk_add_f32 v[114:115], v[122:123], v[114:115]
	v_exp_f32_e32 v126, v126
	v_exp_f32_e32 v127, v127
	v_pk_add_f32 v[114:115], v[124:125], v[114:115]
	v_exp_f32_e32 v128, v128
	v_exp_f32_e32 v129, v129
	v_pk_add_f32 v[114:115], v[126:127], v[114:115]
	v_pk_add_f32 v[116:117], v[128:129], v[114:115]
	v_exp_f32_e32 v114, v98
	v_exp_f32_e32 v115, v99
	s_nop 0
	v_pk_add_f32 v[98:99], v[114:115], v[116:117]
	v_exp_f32_e32 v116, v100
	v_exp_f32_e32 v117, v101
	v_exp_f32_e32 v118, v102
	v_exp_f32_e32 v119, v103
	v_pk_add_f32 v[98:99], v[116:117], v[98:99]
	v_exp_f32_e32 v120, v104
	v_exp_f32_e32 v121, v105
	v_pk_add_f32 v[98:99], v[118:119], v[98:99]
	v_or_b32_e32 v207, s31, v202
	v_pk_add_f32 v[100:101], v[120:121], v[98:99]
	s_nop 0
	v_exp_f32_e32 v98, v106
	v_exp_f32_e32 v99, v107
	s_nop 0
	v_pk_add_f32 v[102:103], v[98:99], v[100:101]
	v_mov_b32_e32 v100, v108
	v_exp_f32_e32 v108, v84
	v_exp_f32_e32 v100, v100
	v_exp_f32_e32 v101, v109
	v_exp_f32_e32 v109, v85
	v_pk_add_f32 v[104:105], v[100:101], v[102:103]
	v_mov_b32_e32 v102, v110
	v_exp_f32_e32 v110, v86
	v_exp_f32_e32 v102, v102
	v_exp_f32_e32 v103, v111
	v_exp_f32_e32 v111, v87
	v_pk_add_f32 v[106:107], v[102:103], v[104:105]
	v_mov_b32_e32 v104, v112
	v_exp_f32_e32 v112, v88
	v_exp_f32_e32 v104, v104
	v_exp_f32_e32 v105, v113
	v_exp_f32_e32 v113, v89
	v_pk_add_f32 v[106:107], v[104:105], v[106:107]
	s_nop 0
	v_add_f32_e32 v106, v106, v107
	v_add_f32_e32 v201, v201, v106
	v_exp_f32_e32 v106, v82
	v_exp_f32_e32 v107, v83
	v_exp_f32_e32 v90, v90
	v_exp_f32_e32 v91, v91
	v_pk_add_f32 v[82:83], v[106:107], 0 op_sel_hi:[1,0]
	v_exp_f32_e32 v92, v92
	v_pk_add_f32 v[82:83], v[108:109], v[82:83]
	v_exp_f32_e32 v93, v93
	v_pk_add_f32 v[82:83], v[110:111], v[82:83]
	v_exp_f32_e32 v94, v94
	v_exp_f32_e32 v95, v95
	v_pk_add_f32 v[82:83], v[112:113], v[82:83]
	v_exp_f32_e32 v96, v96
	v_exp_f32_e32 v97, v97
	v_pk_add_f32 v[82:83], v[90:91], v[82:83]
	s_nop 0
	v_pk_add_f32 v[82:83], v[92:93], v[82:83]
	s_nop 0
	v_pk_add_f32 v[82:83], v[94:95], v[82:83]
	s_nop 0
	v_pk_add_f32 v[84:85], v[96:97], v[82:83]
	v_exp_f32_e32 v82, v66
	v_exp_f32_e32 v83, v67
	s_nop 0
	v_pk_add_f32 v[66:67], v[82:83], v[84:85]
	v_exp_f32_e32 v84, v68
	v_exp_f32_e32 v85, v69
	s_nop 0
	v_pk_add_f32 v[66:67], v[84:85], v[66:67]
	v_exp_f32_e32 v86, v70
	v_exp_f32_e32 v87, v71
	s_nop 0
	v_pk_add_f32 v[66:67], v[86:87], v[66:67]
	v_exp_f32_e32 v88, v72
	v_exp_f32_e32 v89, v73
	s_nop 0
	v_pk_add_f32 v[68:69], v[88:89], v[66:67]
	s_nop 0
	v_exp_f32_e32 v66, v74
	v_exp_f32_e32 v67, v75
	s_nop 0
	v_pk_add_f32 v[70:71], v[66:67], v[68:69]
	s_nop 0
	v_exp_f32_e32 v68, v76
	v_exp_f32_e32 v69, v77
	s_nop 0
	v_pk_add_f32 v[72:73], v[68:69], v[70:71]
	s_nop 0
	v_exp_f32_e32 v70, v78
	v_exp_f32_e32 v71, v79
	s_nop 0
	v_pk_add_f32 v[74:75], v[70:71], v[72:73]
	s_nop 0
	v_exp_f32_e32 v72, v80
	v_exp_f32_e32 v73, v81
	s_nop 0
	v_pk_add_f32 v[74:75], v[72:73], v[74:75]
	s_nop 0
	v_add_f32_e32 v74, v74, v75
	v_add_f32_e32 v199, v199, v74
	s_branch .Laf_pv_mix2
.Laf_slow_mix2:
	v_pk_add_f32 v[114:115], v[114:115], v[186:187] op_sel_hi:[1,0] neg_lo:[0,1] neg_hi:[0,1]
	v_pk_add_f32 v[116:117], v[116:117], v[186:187] op_sel_hi:[1,0] neg_lo:[0,1] neg_hi:[0,1]
	v_exp_f32_e32 v190, v114
	v_exp_f32_e32 v191, v115
	v_exp_f32_e32 v192, v116
	v_exp_f32_e32 v193, v117
	v_pk_add_f32 v[116:117], v[118:119], v[186:187] op_sel_hi:[1,0] neg_lo:[0,1] neg_hi:[0,1]
	v_pk_add_f32 v[114:115], v[190:191], 0 op_sel_hi:[1,0]
	v_exp_f32_e32 v194, v116
	v_exp_f32_e32 v195, v117
	v_pk_add_f32 v[116:117], v[120:121], v[186:187] op_sel_hi:[1,0] neg_lo:[0,1] neg_hi:[0,1]
	v_pk_add_f32 v[114:115], v[192:193], v[114:115]
	v_exp_f32_e32 v196, v116
	v_exp_f32_e32 v197, v117
	v_pk_add_f32 v[116:117], v[122:123], v[186:187] op_sel_hi:[1,0] neg_lo:[0,1] neg_hi:[0,1]
	v_pk_add_f32 v[114:115], v[194:195], v[114:115]
	v_exp_f32_e32 v122, v116
	v_exp_f32_e32 v123, v117
	v_pk_add_f32 v[116:117], v[124:125], v[186:187] op_sel_hi:[1,0] neg_lo:[0,1] neg_hi:[0,1]
	v_pk_add_f32 v[114:115], v[196:197], v[114:115]
	v_exp_f32_e32 v124, v116
	v_exp_f32_e32 v125, v117
	v_pk_add_f32 v[116:117], v[126:127], v[186:187] op_sel_hi:[1,0] neg_lo:[0,1] neg_hi:[0,1]
	v_pk_add_f32 v[114:115], v[122:123], v[114:115]
	v_exp_f32_e32 v126, v116
	v_exp_f32_e32 v127, v117
	v_pk_add_f32 v[116:117], v[128:129], v[186:187] op_sel_hi:[1,0] neg_lo:[0,1] neg_hi:[0,1]
	v_pk_add_f32 v[114:115], v[124:125], v[114:115]
	v_exp_f32_e32 v128, v116
	v_exp_f32_e32 v129, v117
	v_pk_add_f32 v[114:115], v[126:127], v[114:115]
	v_pk_add_f32 v[98:99], v[98:99], v[186:187] op_sel_hi:[1,0] neg_lo:[0,1] neg_hi:[0,1]
	v_pk_add_f32 v[100:101], v[100:101], v[186:187] op_sel_hi:[1,0] neg_lo:[0,1] neg_hi:[0,1]
	v_pk_add_f32 v[116:117], v[128:129], v[114:115]
	v_exp_f32_e32 v114, v98
	v_exp_f32_e32 v115, v99
	v_pk_add_f32 v[82:83], v[82:83], v[188:189] op_sel_hi:[1,0] neg_lo:[0,1] neg_hi:[0,1]
	v_pk_add_f32 v[84:85], v[84:85], v[188:189] op_sel_hi:[1,0] neg_lo:[0,1] neg_hi:[0,1]
	v_pk_add_f32 v[66:67], v[66:67], v[188:189] op_sel_hi:[1,0] neg_lo:[0,1] neg_hi:[0,1]
	v_pk_add_f32 v[98:99], v[114:115], v[116:117]
	v_exp_f32_e32 v116, v100
	v_exp_f32_e32 v117, v101
	v_pk_add_f32 v[100:101], v[102:103], v[186:187] op_sel_hi:[1,0] neg_lo:[0,1] neg_hi:[0,1]
	v_pk_add_f32 v[68:69], v[68:69], v[188:189] op_sel_hi:[1,0] neg_lo:[0,1] neg_hi:[0,1]
	v_exp_f32_e32 v118, v100
	v_exp_f32_e32 v119, v101
	v_pk_add_f32 v[100:101], v[104:105], v[186:187] op_sel_hi:[1,0] neg_lo:[0,1] neg_hi:[0,1]
	v_pk_add_f32 v[98:99], v[116:117], v[98:99]
	v_exp_f32_e32 v120, v100
	v_exp_f32_e32 v121, v101
	v_pk_add_f32 v[98:99], v[118:119], v[98:99]
	v_or_b32_e32 v207, s31, v202
	v_pk_add_f32 v[100:101], v[120:121], v[98:99]
	v_pk_add_f32 v[98:99], v[106:107], v[186:187] op_sel_hi:[1,0] neg_lo:[0,1] neg_hi:[0,1]
	s_nop 0
	v_exp_f32_e32 v98, v98
	v_exp_f32_e32 v99, v99
	s_nop 0
	v_pk_add_f32 v[102:103], v[98:99], v[100:101]
	v_pk_add_f32 v[100:101], v[108:109], v[186:187] op_sel_hi:[1,0] neg_lo:[0,1] neg_hi:[0,1]
	v_exp_f32_e32 v108, v84
	v_exp_f32_e32 v100, v100
	v_exp_f32_e32 v101, v101
	v_exp_f32_e32 v109, v85
	v_pk_add_f32 v[84:85], v[86:87], v[188:189] op_sel_hi:[1,0] neg_lo:[0,1] neg_hi:[0,1]
	v_pk_add_f32 v[104:105], v[100:101], v[102:103]
	v_pk_add_f32 v[102:103], v[110:111], v[186:187] op_sel_hi:[1,0] neg_lo:[0,1] neg_hi:[0,1]
	v_exp_f32_e32 v110, v84
	v_exp_f32_e32 v102, v102
	v_exp_f32_e32 v103, v103
	v_exp_f32_e32 v111, v85
	v_pk_add_f32 v[84:85], v[88:89], v[188:189] op_sel_hi:[1,0] neg_lo:[0,1] neg_hi:[0,1]
	v_pk_add_f32 v[106:107], v[102:103], v[104:105]
	v_pk_add_f32 v[104:105], v[112:113], v[186:187] op_sel_hi:[1,0] neg_lo:[0,1] neg_hi:[0,1]
	v_exp_f32_e32 v112, v84
	v_exp_f32_e32 v104, v104
	v_exp_f32_e32 v105, v105
	v_exp_f32_e32 v113, v85
	v_pk_add_f32 v[84:85], v[90:91], v[188:189] op_sel_hi:[1,0] neg_lo:[0,1] neg_hi:[0,1]
	v_pk_add_f32 v[106:107], v[104:105], v[106:107]
	s_nop 0
	v_add_f32_e32 v106, v106, v107
	v_add_f32_e32 v201, v201, v106
	v_exp_f32_e32 v106, v82
	v_exp_f32_e32 v107, v83
	v_exp_f32_e32 v90, v84
	v_exp_f32_e32 v91, v85
	v_pk_add_f32 v[84:85], v[92:93], v[188:189] op_sel_hi:[1,0] neg_lo:[0,1] neg_hi:[0,1]
	v_pk_add_f32 v[82:83], v[106:107], 0 op_sel_hi:[1,0]
	v_exp_f32_e32 v92, v84
	v_pk_add_f32 v[82:83], v[108:109], v[82:83]
	v_exp_f32_e32 v93, v85
	v_pk_add_f32 v[84:85], v[94:95], v[188:189] op_sel_hi:[1,0] neg_lo:[0,1] neg_hi:[0,1]
	v_pk_add_f32 v[82:83], v[110:111], v[82:83]
	v_exp_f32_e32 v94, v84
	v_exp_f32_e32 v95, v85
	v_pk_add_f32 v[84:85], v[96:97], v[188:189] op_sel_hi:[1,0] neg_lo:[0,1] neg_hi:[0,1]
	v_pk_add_f32 v[82:83], v[112:113], v[82:83]
	v_exp_f32_e32 v96, v84
	v_exp_f32_e32 v97, v85
	v_pk_add_f32 v[82:83], v[90:91], v[82:83]
	s_nop 0
	v_pk_add_f32 v[82:83], v[92:93], v[82:83]
	s_nop 0
	v_pk_add_f32 v[82:83], v[94:95], v[82:83]
	s_nop 0
	v_pk_add_f32 v[84:85], v[96:97], v[82:83]
	v_exp_f32_e32 v82, v66
	v_exp_f32_e32 v83, v67
	s_nop 0
	v_pk_add_f32 v[66:67], v[82:83], v[84:85]
	v_exp_f32_e32 v84, v68
	v_exp_f32_e32 v85, v69
	v_pk_add_f32 v[68:69], v[70:71], v[188:189] op_sel_hi:[1,0] neg_lo:[0,1] neg_hi:[0,1]
	v_pk_add_f32 v[66:67], v[84:85], v[66:67]
	v_exp_f32_e32 v86, v68
	v_exp_f32_e32 v87, v69
	v_pk_add_f32 v[68:69], v[72:73], v[188:189] op_sel_hi:[1,0] neg_lo:[0,1] neg_hi:[0,1]
	v_pk_add_f32 v[66:67], v[86:87], v[66:67]
	v_exp_f32_e32 v88, v68
	v_exp_f32_e32 v89, v69
	s_nop 0
	v_pk_add_f32 v[68:69], v[88:89], v[66:67]
	v_pk_add_f32 v[66:67], v[74:75], v[188:189] op_sel_hi:[1,0] neg_lo:[0,1] neg_hi:[0,1]
	s_nop 0
	v_exp_f32_e32 v66, v66
	v_exp_f32_e32 v67, v67
	s_nop 0
	v_pk_add_f32 v[70:71], v[66:67], v[68:69]
	v_pk_add_f32 v[68:69], v[76:77], v[188:189] op_sel_hi:[1,0] neg_lo:[0,1] neg_hi:[0,1]
	s_nop 0
	v_exp_f32_e32 v68, v68
	v_exp_f32_e32 v69, v69
	s_nop 0
	v_pk_add_f32 v[72:73], v[68:69], v[70:71]
	v_pk_add_f32 v[70:71], v[78:79], v[188:189] op_sel_hi:[1,0] neg_lo:[0,1] neg_hi:[0,1]
	s_nop 0
	v_exp_f32_e32 v70, v70
	v_exp_f32_e32 v71, v71
	s_nop 0
	v_pk_add_f32 v[74:75], v[70:71], v[72:73]
	v_pk_add_f32 v[72:73], v[80:81], v[188:189] op_sel_hi:[1,0] neg_lo:[0,1] neg_hi:[0,1]
	s_nop 0
	v_exp_f32_e32 v72, v72
	v_exp_f32_e32 v73, v73
	s_nop 0
	v_pk_add_f32 v[74:75], v[72:73], v[74:75]
	s_nop 0
	v_add_f32_e32 v74, v74, v75
	v_add_f32_e32 v199, v199, v74
.Laf_pv_mix2:
	v_cvt_pk_bf16_f32 v74, v190, v191
	v_cvt_pk_bf16_f32 v75, v192, v193
	v_cvt_pk_bf16_f32 v76, v194, v195
	v_cvt_pk_bf16_f32 v77, v196, v197
	v_cvt_pk_bf16_f32 v78, v106, v107
	v_cvt_pk_bf16_f32 v79, v108, v109
	v_cvt_pk_bf16_f32 v80, v110, v111
	v_cvt_pk_bf16_f32 v81, v112, v113
	s_waitcnt lgkmcnt(4)
	v_mfma_f32_32x32x16_bf16 v[50:65], v[226:229], v[74:77], v[50:65]
	v_mfma_f32_32x32x16_bf16 v[18:33], v[226:229], v[78:81], v[18:33]
	ds_read_b64_tr_b16 v[226:227], v225 offset:20800
	ds_read_b64_tr_b16 v[228:229], v225 offset:21952
	s_waitcnt lgkmcnt(4)
	v_mfma_f32_32x32x16_bf16 v[34:49], v[230:233], v[74:77], v[34:49]
	v_cvt_pk_bf16_f32 v74, v122, v123
	v_cvt_pk_bf16_f32 v75, v124, v125
	v_cvt_pk_bf16_f32 v76, v126, v127
	v_cvt_pk_bf16_f32 v77, v128, v129
	v_mfma_f32_32x32x16_bf16 v[2:17], v[230:233], v[78:81], v[2:17]
	v_cvt_pk_bf16_f32 v78, v90, v91
	v_cvt_pk_bf16_f32 v79, v92, v93
	v_cvt_pk_bf16_f32 v80, v94, v95
	v_cvt_pk_bf16_f32 v81, v96, v97
	ds_read_b64_tr_b16 v[230:231], v225 offset:23040
	ds_read_b64_tr_b16 v[232:233], v225 offset:24192
	s_waitcnt lgkmcnt(4)
	v_mfma_f32_32x32x16_bf16 v[50:65], v[234:237], v[74:77], v[50:65]
	v_mfma_f32_32x32x16_bf16 v[18:33], v[234:237], v[78:81], v[18:33]
	ds_read_b64_tr_b16 v[234:235], v225 offset:23104
	ds_read_b64_tr_b16 v[236:237], v225 offset:24256
	s_waitcnt lgkmcnt(4)
	v_mfma_f32_32x32x16_bf16 v[34:49], v[226:229], v[74:77], v[34:49]
	v_cvt_pk_bf16_f32 v74, v114, v115
	v_cvt_pk_bf16_f32 v75, v116, v117
	v_cvt_pk_bf16_f32 v76, v118, v119
	v_cvt_pk_bf16_f32 v77, v120, v121
	v_mfma_f32_32x32x16_bf16 v[2:17], v[226:229], v[78:81], v[2:17]
	v_cvt_pk_bf16_f32 v78, v82, v83
	v_cvt_pk_bf16_f32 v79, v84, v85
	v_cvt_pk_bf16_f32 v80, v86, v87
	v_cvt_pk_bf16_f32 v81, v88, v89
	ds_read_b64_tr_b16 v[226:227], v225 offset:25344
	ds_read_b64_tr_b16 v[228:229], v225 offset:26496
	s_waitcnt lgkmcnt(4)
	v_mfma_f32_32x32x16_bf16 v[50:65], v[230:233], v[74:77], v[50:65]
	v_mfma_f32_32x32x16_bf16 v[18:33], v[230:233], v[78:81], v[18:33]
	ds_read_b64_tr_b16 v[230:231], v225 offset:25408
	ds_read_b64_tr_b16 v[232:233], v225 offset:26560
	s_waitcnt lgkmcnt(4)
	v_mfma_f32_32x32x16_bf16 v[34:49], v[234:237], v[74:77], v[34:49]
	v_cvt_pk_bf16_f32 v74, v98, v99
	v_cvt_pk_bf16_f32 v75, v100, v101
	v_cvt_pk_bf16_f32 v76, v102, v103
	v_cvt_pk_bf16_f32 v77, v104, v105
	v_mfma_f32_32x32x16_bf16 v[2:17], v[234:237], v[78:81], v[2:17]
	v_cvt_pk_bf16_f32 v66, v66, v67
	v_cvt_pk_bf16_f32 v67, v68, v69
	v_cvt_pk_bf16_f32 v68, v70, v71
	v_cvt_pk_bf16_f32 v69, v72, v73
	s_waitcnt lgkmcnt(2)
	v_mfma_f32_32x32x16_bf16 v[50:65], v[226:229], v[74:77], v[50:65]
	v_mfma_f32_32x32x16_bf16 v[18:33], v[226:229], v[66:69], v[18:33]
	s_waitcnt lgkmcnt(0)
	v_mfma_f32_32x32x16_bf16 v[34:49], v[230:233], v[74:77], v[34:49]
	v_mfma_f32_32x32x16_bf16 v[2:17], v[230:233], v[66:69], v[2:17]

.LBB0_358:
	v_and_b32_e32 v197, 63, v201
	s_lshl_b32 s44, s18, 6
	v_cmp_gt_u32_e32 vcc, 32, v197
	v_lshlrev_b32_e32 v214, 3, v3
	s_cmp_gt_u32 s20, 4
	v_cndmask_b32_e64 v212, 0, 1.0, vcc
	s_waitcnt lgkmcnt(0)
	s_barrier
	s_cbranch_scc1 .LBB0_393
	v_writelane_b32 v255, s48, 0
	v_mul_f32_e32 v200, 0x3fb8aa3b, v2
	s_add_i32 s46, s45, 0xffffff80
	v_writelane_b32 v255, s49, 1
	s_add_i32 s47, s45, 0xbf
	s_add_i32 s48, s45, 0xffffffbf
	s_add_i32 s49, s45, 0x41
	v_lshlrev_b32_e32 v2, 2, v3
	v_lshrrev_b32_e32 v3, 2, v201
	s_lshl_b32 s6, s24, 1
	v_and_or_b32 v215, v3, 3, v2
	v_lshlrev_b32_e32 v3, 2, v201
	s_add_u32 s6, s82, s6
	v_and_b32_e32 v16, 16, v201
	v_and_b32_e32 v17, 12, v3
	v_sub_u32_e32 v2, v2, v203
	s_addc_u32 s7, s83, 0
	v_mov_b32_e32 v14, v1
	v_mov_b32_e32 v15, v1
	v_add_u32_e32 v217, 0x80, v2
	v_lshl_add_u64 v[198:199], s[6:7], 0, v[0:1]
	v_mov_b32_e32 v0, v1
	v_mov_b32_e32 v2, v1
	v_mov_b32_e32 v3, v1
	v_mov_b32_e32 v4, v1
	v_mov_b32_e32 v5, v1
	v_mov_b32_e32 v6, v1
	v_mov_b32_e32 v7, v1
	v_mov_b32_e32 v8, v1
	v_mov_b32_e32 v9, v1
	v_mov_b32_e32 v10, v1
	v_mov_b32_e32 v11, v1
	v_mov_b32_e32 v12, v1
	v_mov_b32_e32 v13, v1
	v_lshlrev_b32_e32 v222, 1, v16
	v_lshlrev_b32_e32 v223, 1, v17
	v_mov_b64_e32 v[78:79], v[14:15]
	v_mov_b64_e32 v[46:47], v[14:15]
	v_mov_b64_e32 v[62:63], v[14:15]
	v_mov_b64_e32 v[30:31], v[14:15]
	s_mov_b32 s61, 0
	v_mov_b32_e32 v216, v212
	v_mov_b32_e32 v202, v200
	s_mov_b32 s99, 0x42800000
	v_exp_f32_e32 v220, v200
	v_cmp_lt_f32_e64 vcc, |v200|, s99
	s_nop 1
	v_cndmask_b32_e32 v220, 1.0, v220, vcc
	v_cndmask_b32_e64 v200, v200, 0, vcc
	v_mul_f32_e32 v212, v212, v220
	v_mov_b32_e32 v216, v212
	v_mov_b32_e32 v202, v200
	v_mov_b64_e32 v[76:77], v[12:13]
	v_mov_b64_e32 v[74:75], v[10:11]
	v_mov_b64_e32 v[72:73], v[8:9]
	v_mov_b64_e32 v[70:71], v[6:7]
	v_mov_b64_e32 v[68:69], v[4:5]
	v_mov_b64_e32 v[66:67], v[2:3]
	v_mov_b64_e32 v[64:65], v[0:1]
	v_mov_b64_e32 v[44:45], v[12:13]
	v_mov_b64_e32 v[42:43], v[10:11]
	v_mov_b64_e32 v[40:41], v[8:9]
	v_mov_b64_e32 v[38:39], v[6:7]
	v_mov_b64_e32 v[36:37], v[4:5]
	v_mov_b64_e32 v[34:35], v[2:3]
	v_mov_b64_e32 v[32:33], v[0:1]
	v_mov_b64_e32 v[60:61], v[12:13]
	v_mov_b64_e32 v[58:59], v[10:11]
	v_mov_b64_e32 v[56:57], v[8:9]
	v_mov_b64_e32 v[54:55], v[6:7]
	v_mov_b64_e32 v[52:53], v[4:5]
	v_mov_b64_e32 v[50:51], v[2:3]
	v_mov_b64_e32 v[48:49], v[0:1]
	v_mov_b64_e32 v[28:29], v[12:13]
	v_mov_b64_e32 v[26:27], v[10:11]
	v_mov_b64_e32 v[24:25], v[8:9]
	v_mov_b64_e32 v[22:23], v[6:7]
	v_mov_b64_e32 v[20:21], v[4:5]
	v_mov_b64_e32 v[18:19], v[2:3]
	v_mov_b64_e32 v[16:17], v[0:1]
	v_readfirstlane_b32 s99, v244
	s_lshr_b32 s99, s99, 8
	s_cmp_eq_u32 s99, 1
	s_cbranch_scc0 .Lap_skip_mix1
	s_setprio 1

.LBB0_378:
	v_or_b32_e32 v221, s35, v215
	v_mad_u32_u24 v225, v221, s89, v224
	ds_read_b64_tr_b16 v[226:227], v225 offset:18432
	ds_read_b64_tr_b16 v[228:229], v225 offset:19584
	ds_read_b64_tr_b16 v[230:231], v225 offset:18496
	ds_read_b64_tr_b16 v[232:233], v225 offset:19648
	ds_read_b64_tr_b16 v[234:235], v225 offset:20736
	ds_read_b64_tr_b16 v[236:237], v225 offset:21888
	v_or_b32_e32 v220, v200, v202
	v_cmp_ne_u32_e32 vcc, 0, v220
	s_cbranch_vccnz .Laf_slow_mix1
	v_exp_f32_e32 v204, v128
	v_exp_f32_e32 v205, v129
	v_exp_f32_e32 v206, v130
	v_exp_f32_e32 v207, v131
	v_pk_add_f32 v[2:3], v[204:205], 0 op_sel_hi:[1,0]
	v_exp_f32_e32 v208, v132
	v_exp_f32_e32 v209, v133
	v_pk_add_f32 v[2:3], v[206:207], v[2:3]
	v_exp_f32_e32 v210, v134
	v_exp_f32_e32 v211, v135
	v_pk_add_f32 v[2:3], v[208:209], v[2:3]
	v_exp_f32_e32 v128, v136
	v_exp_f32_e32 v129, v137
	v_pk_add_f32 v[2:3], v[210:211], v[2:3]
	v_exp_f32_e32 v130, v138
	v_exp_f32_e32 v131, v139
	v_pk_add_f32 v[2:3], v[128:129], v[2:3]
	v_exp_f32_e32 v132, v140
	v_exp_f32_e32 v133, v141
	v_pk_add_f32 v[2:3], v[130:131], v[2:3]
	v_exp_f32_e32 v134, v142
	v_exp_f32_e32 v135, v143
	v_pk_add_f32 v[2:3], v[132:133], v[2:3]
	v_exp_f32_e32 v10, v112
	v_exp_f32_e32 v11, v113
	v_pk_add_f32 v[2:3], v[134:135], v[2:3]
	v_exp_f32_e32 v12, v114
	v_exp_f32_e32 v13, v115
	v_pk_add_f32 v[2:3], v[10:11], v[2:3]
	v_exp_f32_e32 v14, v116
	v_exp_f32_e32 v15, v117
	v_pk_add_f32 v[2:3], v[12:13], v[2:3]
	v_exp_f32_e32 v112, v118
	v_exp_f32_e32 v113, v119
	v_pk_add_f32 v[2:3], v[14:15], v[2:3]
	v_pk_add_f32 v[4:5], v[112:113], v[2:3]
	s_nop 0
	v_exp_f32_e32 v2, v120
	v_exp_f32_e32 v3, v121
	s_nop 0
	v_pk_add_f32 v[6:7], v[2:3], v[4:5]
	v_mov_b32_e32 v4, v122
	v_exp_f32_e32 v122, v80
	v_exp_f32_e32 v4, v4
	v_exp_f32_e32 v5, v123
	v_exp_f32_e32 v123, v81
	v_pk_add_f32 v[8:9], v[4:5], v[6:7]
	v_mov_b32_e32 v6, v124
	v_exp_f32_e32 v124, v82
	v_exp_f32_e32 v6, v6
	v_exp_f32_e32 v7, v125
	v_exp_f32_e32 v125, v83
	v_pk_add_f32 v[80:81], v[122:123], 0 op_sel_hi:[1,0]
	v_pk_add_f32 v[114:115], v[6:7], v[8:9]
	v_mov_b32_e32 v8, v126
	v_exp_f32_e32 v126, v84
	v_exp_f32_e32 v8, v8
	v_exp_f32_e32 v9, v127
	v_exp_f32_e32 v127, v85
	v_pk_add_f32 v[80:81], v[124:125], v[80:81]
	v_pk_add_f32 v[114:115], v[8:9], v[114:115]
	v_exp_f32_e32 v136, v86
	v_add_f32_e32 v114, v114, v115
	v_exp_f32_e32 v137, v87
	v_add_f32_e32 v216, v216, v114
	v_exp_f32_e32 v114, v88
	v_exp_f32_e32 v115, v89
	v_pk_add_f32 v[80:81], v[126:127], v[80:81]
	v_exp_f32_e32 v116, v90
	v_exp_f32_e32 v117, v91
	v_pk_add_f32 v[80:81], v[136:137], v[80:81]
	v_exp_f32_e32 v118, v92
	v_exp_f32_e32 v119, v93
	v_pk_add_f32 v[80:81], v[114:115], v[80:81]
	v_exp_f32_e32 v120, v94
	v_exp_f32_e32 v121, v95
	v_pk_add_f32 v[80:81], v[116:117], v[80:81]
	v_exp_f32_e32 v88, v96
	v_exp_f32_e32 v89, v97
	v_pk_add_f32 v[80:81], v[118:119], v[80:81]
	v_exp_f32_e32 v90, v98
	v_exp_f32_e32 v91, v99
	v_pk_add_f32 v[80:81], v[120:121], v[80:81]
	v_exp_f32_e32 v92, v100
	v_exp_f32_e32 v93, v101
	v_pk_add_f32 v[80:81], v[88:89], v[80:81]
	v_exp_f32_e32 v94, v102
	v_exp_f32_e32 v95, v103
	v_pk_add_f32 v[80:81], v[90:91], v[80:81]
	s_nop 0
	v_pk_add_f32 v[80:81], v[92:93], v[80:81]
	s_nop 0
	v_pk_add_f32 v[82:83], v[94:95], v[80:81]
	v_mov_b32_e32 v80, v104
	v_or_b32_e32 v104, s35, v215
	v_exp_f32_e32 v80, v80
	v_exp_f32_e32 v81, v105
	s_nop 0
	v_pk_add_f32 v[84:85], v[80:81], v[82:83]
	s_nop 0
	v_exp_f32_e32 v82, v106
	v_exp_f32_e32 v83, v107
	s_nop 0
	v_pk_add_f32 v[86:87], v[82:83], v[84:85]
	v_exp_f32_e32 v84, v108
	v_exp_f32_e32 v85, v109
	s_nop 0
	v_pk_add_f32 v[96:97], v[84:85], v[86:87]
	s_nop 0
	v_exp_f32_e32 v86, v110
	v_exp_f32_e32 v87, v111
	s_nop 0
	v_pk_add_f32 v[96:97], v[86:87], v[96:97]
	s_nop 0
	v_add_f32_e32 v96, v96, v97
	v_add_f32_e32 v212, v212, v96
	s_branch .Laf_pv_mix1
.Laf_slow_mix1:
	v_pk_add_f32 v[2:3], v[128:129], v[200:201] op_sel_hi:[1,0] neg_lo:[0,1] neg_hi:[0,1]
	v_pk_add_f32 v[4:5], v[130:131], v[200:201] op_sel_hi:[1,0] neg_lo:[0,1] neg_hi:[0,1]
	v_exp_f32_e32 v204, v2
	v_exp_f32_e32 v205, v3
	v_exp_f32_e32 v206, v4
	v_exp_f32_e32 v207, v5
	v_pk_add_f32 v[4:5], v[132:133], v[200:201] op_sel_hi:[1,0] neg_lo:[0,1] neg_hi:[0,1]
	v_pk_add_f32 v[2:3], v[204:205], 0 op_sel_hi:[1,0]
	v_exp_f32_e32 v208, v4
	v_exp_f32_e32 v209, v5
	v_pk_add_f32 v[4:5], v[134:135], v[200:201] op_sel_hi:[1,0] neg_lo:[0,1] neg_hi:[0,1]
	v_pk_add_f32 v[2:3], v[206:207], v[2:3]
	v_exp_f32_e32 v210, v4
	v_exp_f32_e32 v211, v5
	v_pk_add_f32 v[4:5], v[136:137], v[200:201] op_sel_hi:[1,0] neg_lo:[0,1] neg_hi:[0,1]
	v_pk_add_f32 v[2:3], v[208:209], v[2:3]
	v_exp_f32_e32 v128, v4
	v_exp_f32_e32 v129, v5
	v_pk_add_f32 v[4:5], v[138:139], v[200:201] op_sel_hi:[1,0] neg_lo:[0,1] neg_hi:[0,1]
	v_pk_add_f32 v[2:3], v[210:211], v[2:3]
	v_exp_f32_e32 v130, v4
	v_exp_f32_e32 v131, v5
	v_pk_add_f32 v[4:5], v[140:141], v[200:201] op_sel_hi:[1,0] neg_lo:[0,1] neg_hi:[0,1]
	v_pk_add_f32 v[2:3], v[128:129], v[2:3]
	v_exp_f32_e32 v132, v4
	v_exp_f32_e32 v133, v5
	v_pk_add_f32 v[4:5], v[142:143], v[200:201] op_sel_hi:[1,0] neg_lo:[0,1] neg_hi:[0,1]
	v_pk_add_f32 v[2:3], v[130:131], v[2:3]
	v_exp_f32_e32 v134, v4
	v_exp_f32_e32 v135, v5
	v_pk_add_f32 v[4:5], v[112:113], v[200:201] op_sel_hi:[1,0] neg_lo:[0,1] neg_hi:[0,1]
	v_pk_add_f32 v[2:3], v[132:133], v[2:3]
	v_exp_f32_e32 v10, v4
	v_exp_f32_e32 v11, v5
	v_pk_add_f32 v[4:5], v[114:115], v[200:201] op_sel_hi:[1,0] neg_lo:[0,1] neg_hi:[0,1]
	v_pk_add_f32 v[2:3], v[134:135], v[2:3]
	v_exp_f32_e32 v12, v4
	v_exp_f32_e32 v13, v5
	v_pk_add_f32 v[4:5], v[116:117], v[200:201] op_sel_hi:[1,0] neg_lo:[0,1] neg_hi:[0,1]
	v_pk_add_f32 v[2:3], v[10:11], v[2:3]
	v_exp_f32_e32 v14, v4
	v_exp_f32_e32 v15, v5
	v_pk_add_f32 v[4:5], v[118:119], v[200:201] op_sel_hi:[1,0] neg_lo:[0,1] neg_hi:[0,1]
	v_pk_add_f32 v[2:3], v[12:13], v[2:3]
	v_exp_f32_e32 v112, v4
	v_exp_f32_e32 v113, v5
	v_pk_add_f32 v[2:3], v[14:15], v[2:3]
	v_pk_add_f32 v[80:81], v[80:81], v[202:203] op_sel_hi:[1,0] neg_lo:[0,1] neg_hi:[0,1]
	v_pk_add_f32 v[82:83], v[82:83], v[202:203] op_sel_hi:[1,0] neg_lo:[0,1] neg_hi:[0,1]
	v_pk_add_f32 v[4:5], v[112:113], v[2:3]
	v_pk_add_f32 v[2:3], v[120:121], v[200:201] op_sel_hi:[1,0] neg_lo:[0,1] neg_hi:[0,1]
	s_nop 0
	v_exp_f32_e32 v2, v2
	v_exp_f32_e32 v3, v3
	s_nop 0
	v_pk_add_f32 v[6:7], v[2:3], v[4:5]
	v_pk_add_f32 v[4:5], v[122:123], v[200:201] op_sel_hi:[1,0] neg_lo:[0,1] neg_hi:[0,1]
	v_exp_f32_e32 v122, v80
	v_exp_f32_e32 v4, v4
	v_exp_f32_e32 v5, v5
	v_exp_f32_e32 v123, v81
	v_pk_add_f32 v[8:9], v[4:5], v[6:7]
	v_pk_add_f32 v[6:7], v[124:125], v[200:201] op_sel_hi:[1,0] neg_lo:[0,1] neg_hi:[0,1]
	v_exp_f32_e32 v124, v82
	v_exp_f32_e32 v6, v6
	v_exp_f32_e32 v7, v7
	v_exp_f32_e32 v125, v83
	v_pk_add_f32 v[82:83], v[84:85], v[202:203] op_sel_hi:[1,0] neg_lo:[0,1] neg_hi:[0,1]
	v_pk_add_f32 v[80:81], v[122:123], 0 op_sel_hi:[1,0]
	v_pk_add_f32 v[114:115], v[6:7], v[8:9]
	v_pk_add_f32 v[8:9], v[126:127], v[200:201] op_sel_hi:[1,0] neg_lo:[0,1] neg_hi:[0,1]
	v_exp_f32_e32 v126, v82
	v_exp_f32_e32 v8, v8
	v_exp_f32_e32 v9, v9
	v_exp_f32_e32 v127, v83
	v_pk_add_f32 v[82:83], v[86:87], v[202:203] op_sel_hi:[1,0] neg_lo:[0,1] neg_hi:[0,1]
	v_pk_add_f32 v[80:81], v[124:125], v[80:81]
	v_pk_add_f32 v[114:115], v[8:9], v[114:115]
	v_exp_f32_e32 v136, v82
	v_add_f32_e32 v114, v114, v115
	v_exp_f32_e32 v137, v83
	v_pk_add_f32 v[82:83], v[88:89], v[202:203] op_sel_hi:[1,0] neg_lo:[0,1] neg_hi:[0,1]
	v_add_f32_e32 v216, v216, v114
	v_exp_f32_e32 v114, v82
	v_exp_f32_e32 v115, v83
	v_pk_add_f32 v[82:83], v[90:91], v[202:203] op_sel_hi:[1,0] neg_lo:[0,1] neg_hi:[0,1]
	v_pk_add_f32 v[80:81], v[126:127], v[80:81]
	v_exp_f32_e32 v116, v82
	v_exp_f32_e32 v117, v83
	v_pk_add_f32 v[82:83], v[92:93], v[202:203] op_sel_hi:[1,0] neg_lo:[0,1] neg_hi:[0,1]
	v_pk_add_f32 v[80:81], v[136:137], v[80:81]
	v_exp_f32_e32 v118, v82
	v_exp_f32_e32 v119, v83
	v_pk_add_f32 v[82:83], v[94:95], v[202:203] op_sel_hi:[1,0] neg_lo:[0,1] neg_hi:[0,1]
	v_pk_add_f32 v[80:81], v[114:115], v[80:81]
	v_exp_f32_e32 v120, v82
	v_exp_f32_e32 v121, v83
	v_pk_add_f32 v[82:83], v[96:97], v[202:203] op_sel_hi:[1,0] neg_lo:[0,1] neg_hi:[0,1]
	v_pk_add_f32 v[80:81], v[116:117], v[80:81]
	v_exp_f32_e32 v88, v82
	v_exp_f32_e32 v89, v83
	v_pk_add_f32 v[82:83], v[98:99], v[202:203] op_sel_hi:[1,0] neg_lo:[0,1] neg_hi:[0,1]
	v_pk_add_f32 v[80:81], v[118:119], v[80:81]
	v_exp_f32_e32 v90, v82
	v_exp_f32_e32 v91, v83
	v_pk_add_f32 v[82:83], v[100:101], v[202:203] op_sel_hi:[1,0] neg_lo:[0,1] neg_hi:[0,1]
	v_pk_add_f32 v[80:81], v[120:121], v[80:81]
	v_exp_f32_e32 v92, v82
	v_exp_f32_e32 v93, v83
	v_pk_add_f32 v[82:83], v[102:103], v[202:203] op_sel_hi:[1,0] neg_lo:[0,1] neg_hi:[0,1]
	v_pk_add_f32 v[80:81], v[88:89], v[80:81]
	v_exp_f32_e32 v94, v82
	v_exp_f32_e32 v95, v83
	v_pk_add_f32 v[80:81], v[90:91], v[80:81]
	s_nop 0
	v_pk_add_f32 v[80:81], v[92:93], v[80:81]
	s_nop 0
	v_pk_add_f32 v[82:83], v[94:95], v[80:81]
	v_pk_add_f32 v[80:81], v[104:105], v[202:203] op_sel_hi:[1,0] neg_lo:[0,1] neg_hi:[0,1]
	v_or_b32_e32 v104, s35, v215
	v_exp_f32_e32 v80, v80
	v_exp_f32_e32 v81, v81
	s_nop 0
	v_pk_add_f32 v[84:85], v[80:81], v[82:83]
	v_pk_add_f32 v[82:83], v[106:107], v[202:203] op_sel_hi:[1,0] neg_lo:[0,1] neg_hi:[0,1]
	s_nop 0
	v_exp_f32_e32 v82, v82
	v_exp_f32_e32 v83, v83
	s_nop 0
	v_pk_add_f32 v[86:87], v[82:83], v[84:85]
	v_pk_add_f32 v[84:85], v[108:109], v[202:203] op_sel_hi:[1,0] neg_lo:[0,1] neg_hi:[0,1]
	v_exp_f32_e32 v84, v84
	v_exp_f32_e32 v85, v85
	s_nop 0
	v_pk_add_f32 v[96:97], v[84:85], v[86:87]
	v_pk_add_f32 v[86:87], v[110:111], v[202:203] op_sel_hi:[1,0] neg_lo:[0,1] neg_hi:[0,1]
	s_nop 0
	v_exp_f32_e32 v86, v86
	v_exp_f32_e32 v87, v87
	s_nop 0
	v_pk_add_f32 v[96:97], v[86:87], v[96:97]
	s_nop 0
	v_add_f32_e32 v96, v96, v97
	v_add_f32_e32 v212, v212, v96
.Laf_pv_mix1:
	v_cvt_pk_bf16_f32 v96, v204, v205
	v_cvt_pk_bf16_f32 v97, v206, v207
	v_cvt_pk_bf16_f32 v98, v208, v209
	v_cvt_pk_bf16_f32 v99, v210, v211
	v_cvt_pk_bf16_f32 v100, v122, v123
	v_cvt_pk_bf16_f32 v101, v124, v125
	v_cvt_pk_bf16_f32 v102, v126, v127
	v_cvt_pk_bf16_f32 v103, v136, v137
	s_waitcnt lgkmcnt(4)
	v_mfma_f32_32x32x16_bf16 v[64:79], v[226:229], v[96:99], v[64:79]
	v_mfma_f32_32x32x16_bf16 v[32:47], v[226:229], v[100:103], v[32:47]
	ds_read_b64_tr_b16 v[226:227], v225 offset:20800
	ds_read_b64_tr_b16 v[228:229], v225 offset:21952
	s_waitcnt lgkmcnt(4)
	v_mfma_f32_32x32x16_bf16 v[48:63], v[230:233], v[96:99], v[48:63]
	v_cvt_pk_bf16_f32 v96, v128, v129
	v_cvt_pk_bf16_f32 v97, v130, v131
	v_cvt_pk_bf16_f32 v98, v132, v133
	v_cvt_pk_bf16_f32 v99, v134, v135
	v_mfma_f32_32x32x16_bf16 v[16:31], v[230:233], v[100:103], v[16:31]
	v_cvt_pk_bf16_f32 v100, v114, v115
	v_cvt_pk_bf16_f32 v101, v116, v117
	v_cvt_pk_bf16_f32 v102, v118, v119
	v_cvt_pk_bf16_f32 v103, v120, v121
	ds_read_b64_tr_b16 v[230:231], v225 offset:23040
	ds_read_b64_tr_b16 v[232:233], v225 offset:24192
	s_waitcnt lgkmcnt(4)
	v_mfma_f32_32x32x16_bf16 v[64:79], v[234:237], v[96:99], v[64:79]
	v_mfma_f32_32x32x16_bf16 v[32:47], v[234:237], v[100:103], v[32:47]
	ds_read_b64_tr_b16 v[234:235], v225 offset:23104
	ds_read_b64_tr_b16 v[236:237], v225 offset:24256
	s_waitcnt lgkmcnt(4)
	v_mfma_f32_32x32x16_bf16 v[48:63], v[226:229], v[96:99], v[48:63]
	v_cvt_pk_bf16_f32 v10, v10, v11
	v_cvt_pk_bf16_f32 v11, v12, v13
	v_cvt_pk_bf16_f32 v12, v14, v15
	v_cvt_pk_bf16_f32 v13, v112, v113
	v_mfma_f32_32x32x16_bf16 v[16:31], v[226:229], v[100:103], v[16:31]
	v_cvt_pk_bf16_f32 v88, v88, v89
	v_cvt_pk_bf16_f32 v89, v90, v91
	v_cvt_pk_bf16_f32 v90, v92, v93
	v_cvt_pk_bf16_f32 v91, v94, v95
	ds_read_b64_tr_b16 v[226:227], v225 offset:25344
	ds_read_b64_tr_b16 v[228:229], v225 offset:26496
	s_waitcnt lgkmcnt(4)
	v_mfma_f32_32x32x16_bf16 v[64:79], v[230:233], v[10:13], v[64:79]
	v_mfma_f32_32x32x16_bf16 v[32:47], v[230:233], v[88:91], v[32:47]
	ds_read_b64_tr_b16 v[230:231], v225 offset:25408
	ds_read_b64_tr_b16 v[232:233], v225 offset:26560
	s_waitcnt lgkmcnt(4)
	v_mfma_f32_32x32x16_bf16 v[48:63], v[234:237], v[10:13], v[48:63]
	v_cvt_pk_bf16_f32 v2, v2, v3
	v_cvt_pk_bf16_f32 v3, v4, v5
	v_cvt_pk_bf16_f32 v4, v6, v7
	v_cvt_pk_bf16_f32 v5, v8, v9
	v_mfma_f32_32x32x16_bf16 v[16:31], v[234:237], v[88:91], v[16:31]
	v_cvt_pk_bf16_f32 v6, v80, v81
	v_cvt_pk_bf16_f32 v7, v82, v83
	v_cvt_pk_bf16_f32 v8, v84, v85
	v_cvt_pk_bf16_f32 v9, v86, v87
	s_waitcnt lgkmcnt(2)
	v_mfma_f32_32x32x16_bf16 v[64:79], v[226:229], v[2:5], v[64:79]
	v_mfma_f32_32x32x16_bf16 v[32:47], v[226:229], v[6:9], v[32:47]
	s_waitcnt lgkmcnt(0)
	v_mfma_f32_32x32x16_bf16 v[48:63], v[230:233], v[2:5], v[48:63]
	v_mfma_f32_32x32x16_bf16 v[16:31], v[230:233], v[6:9], v[16:31]
